# FINAL-norm loop: second activation load also issued up front (all six row loads in one batch, counted vmcnt)
# speedup vs baseline: 1.0042x; 1.0042x over previous
; DI int tidx() { int t = __builtin_amdgcn_workitem_id_x(); asm volatile("" : "+v"(t)); return t; }
; DI float bflo(unsigned u) { return __uint_as_float(u << 16); }
; DI float bfhi(unsigned u) { return __uint_as_float(u & 0xffff0000u); }
; DI float rstd16(const float* ssq, int m) {
;   float s = 0.f;
; #pragma unroll
;   for (int c = 0; c < 16; ++c) s += ssq[(size_t)c * TP + m];
;   return rsqrtf(s * (1.f / 1024.f) + RMS_EPS);
; }
; DI void final_rows(CP p, int item) {
;   const int lane = tidx() & 63, wv = tidx() >> 6;
;   const int orow = item * 8 + wv;
;   int r;
;   if (orow < 16384) { int s = orow >> 13; r = s * LPR + 16 + (orow & 8191); }
;   else { int x = orow - 16384; int s = x >> 11; r = 2 * LPR + s * LSM + 16 + (x & 2047); }
;   const float rs = rstd16(p.ssq, r);
;   const u16* src = p.hb + (size_t)r * 1024 + lane * 16;
;   uint4 a = *(const uint4*)src, b = *(const uint4*)(src + 8);
;   unsigned w[8] = {a.x, a.y, a.z, a.w, b.x, b.y, b.z, b.w};
;   float* dst = p.out + (size_t)orow * 1024 + lane * 16;
;   const float* gn = p.final_norm + lane * 16;
; #pragma unroll
;   for (int i = 0; i < 4; ++i) {
;     float4 o;
;     o.x = bflo(w[2 * i]) * rs * gn[4 * i]; o.y = bfhi(w[2 * i]) * rs * gn[4 * i + 1];
;     o.z = bflo(w[2 * i + 1]) * rs * gn[4 * i + 2]; o.w = bfhi(w[2 * i + 1]) * rs * gn[4 * i + 3];
;     *(float4*)(dst + 4 * i) = o;
;   }
; }
.LBB0_14:
	s_or_b64 exec, exec, s[8:9]
	s_load_dwordx2 s[8:9], s[0:1], 0x128
	v_and_b32_e32 v5, v5, v2
	v_add3_u32 v4, v5, v4, v3
	v_ashrrev_i32_e32 v5, 31, v4
	v_lshlrev_b32_e32 v0, 4, v0
	s_waitcnt lgkmcnt(0)
	v_lshl_add_u64 v[6:7], v[4:5], 2, s[8:9]
	s_waitcnt vmcnt(2)
	v_add_co_u32_e32 v8, vcc, 0x20000, v6
	v_lshlrev_b64 v[4:5], 11, v[4:5]
	s_nop 0
	v_addc_co_u32_e32 v9, vcc, 0, v7, vcc
	v_add_co_u32_e32 v10, vcc, 0x40000, v6
	s_add_i32 s14, s14, s94
	s_nop 0
	v_addc_co_u32_e32 v11, vcc, 0, v7, vcc
	v_add_co_u32_e32 v12, vcc, 0x60000, v6
	s_add_i32 s11, s11, s10
	s_nop 0
	v_addc_co_u32_e32 v13, vcc, 0, v7, vcc
	v_add_co_u32_e32 v14, vcc, 0x81000, v6
	s_cmpk_gt_i32 s14, 0xfff
	s_nop 0
	v_addc_co_u32_e32 v15, vcc, 0, v7, vcc
	s_waitcnt vmcnt(1)
	v_add_co_u32_e32 v16, vcc, 0xa1000, v6
	s_nop 1
	v_addc_co_u32_e32 v17, vcc, 0, v7, vcc
	v_add_co_u32_e32 v18, vcc, 0xc1000, v6
	s_nop 1
	v_addc_co_u32_e32 v19, vcc, 0, v7, vcc
	s_waitcnt vmcnt(0)
	v_add_co_u32_e32 v20, vcc, 0xe1000, v6
	s_nop 1
	v_addc_co_u32_e32 v21, vcc, 0, v7, vcc
	global_load_dword v3, v[6:7], off
	global_load_dword v22, v[8:9], off offset:1024
	global_load_dword v23, v[10:11], off offset:2048
	global_load_dword v24, v[12:13], off offset:3072
	global_load_dword v25, v[14:15], off
	global_load_dword v26, v[16:17], off offset:1024
	global_load_dword v27, v[18:19], off offset:2048
	global_load_dword v28, v[20:21], off offset:3072
	v_add_co_u32_e32 v8, vcc, 0x102000, v6
	s_waitcnt vmcnt(7)
	v_add_f32_e32 v3, 0, v3
	v_addc_co_u32_e32 v9, vcc, 0, v7, vcc
	v_add_co_u32_e32 v10, vcc, 0x122000, v6
	s_waitcnt vmcnt(6)
	v_add_f32_e32 v3, v3, v22
	v_addc_co_u32_e32 v11, vcc, 0, v7, vcc
	v_add_co_u32_e32 v12, vcc, 0x142000, v6
	s_waitcnt vmcnt(5)
	v_add_f32_e32 v3, v3, v23
	v_addc_co_u32_e32 v13, vcc, 0, v7, vcc
	v_add_co_u32_e32 v14, vcc, 0x162000, v6
	s_waitcnt vmcnt(4)
	v_add_f32_e32 v3, v3, v24
	v_addc_co_u32_e32 v15, vcc, 0, v7, vcc
	v_add_co_u32_e32 v16, vcc, 0x183000, v6
	s_waitcnt vmcnt(3)
	v_add_f32_e32 v3, v3, v25
	v_addc_co_u32_e32 v17, vcc, 0, v7, vcc
	v_add_co_u32_e32 v18, vcc, 0x1a3000, v6
	s_waitcnt vmcnt(2)
	v_add_f32_e32 v3, v3, v26
	v_addc_co_u32_e32 v19, vcc, 0, v7, vcc
	v_add_co_u32_e32 v20, vcc, 0x1c3000, v6
	s_waitcnt vmcnt(1)
	v_add_f32_e32 v3, v3, v27
	v_addc_co_u32_e32 v21, vcc, 0, v7, vcc
	v_add_co_u32_e32 v6, vcc, 0x1e3000, v6
	s_waitcnt vmcnt(0)
	v_add_f32_e32 v3, v3, v28
	v_addc_co_u32_e32 v7, vcc, 0, v7, vcc
	global_load_dword v29, v[8:9], off
	global_load_dword v30, v[10:11], off offset:1024
	global_load_dword v31, v[12:13], off offset:2048
	s_nop 0
	global_load_dword v14, v[14:15], off offset:3072
	s_nop 0
	global_load_dword v15, v[16:17], off
	s_nop 0
	global_load_dword v16, v[18:19], off offset:1024
	global_load_dword v17, v[20:21], off offset:2048
	s_nop 0
	global_load_dword v18, v[6:7], off offset:3072
	s_load_dwordx2 s[8:9], s[0:1], 0xf8
	v_and_b32_e32 v8, 0x3f0, v0
	v_lshlrev_b32_e32 v0, 1, v8
	s_waitcnt lgkmcnt(0)
	v_lshl_add_u64 v[4:5], s[8:9], 0, v[4:5]
	v_lshl_add_u64 v[12:13], v[4:5], 0, v[0:1]
	global_load_dwordx4 v[4:7], v[12:13], off
	global_load_dwordx4 v[212:215], v[12:13], off offset:16
	v_lshlrev_b32_e32 v0, 2, v8
	global_load_dwordx4 v[8:11], v0, s[40:41]
	global_load_dwordx4 v[200:203], v0, s[40:41] offset:16
	global_load_dwordx4 v[204:207], v0, s[40:41] offset:32
	global_load_dwordx4 v[208:211], v0, s[40:41] offset:48
	s_mov_b32 s8, 0x800000
	s_waitcnt vmcnt(13)
	v_add_f32_e32 v3, v3, v29
	s_waitcnt vmcnt(12)
	v_add_f32_e32 v3, v3, v30
	s_waitcnt vmcnt(11)
	v_add_f32_e32 v3, v3, v31
	s_waitcnt vmcnt(10)
	v_add_f32_e32 v3, v3, v14
	s_waitcnt vmcnt(9)
	v_add_f32_e32 v3, v3, v15
	s_waitcnt vmcnt(8)
	v_add_f32_e32 v3, v3, v16
	s_waitcnt vmcnt(7)
	v_add_f32_e32 v3, v3, v17
	s_waitcnt vmcnt(6)
	v_add_f32_e32 v3, v3, v18
	v_fmamk_f32 v3, v3, 0x3a800000, v180
	v_mul_f32_e32 v14, 0x4b800000, v3
	v_cmp_gt_f32_e32 vcc, s8, v3
	s_nop 1
	v_cndmask_b32_e32 v3, v3, v14, vcc
	v_rsq_f32_e32 v3, v3
	v_mul_f32_e32 v16, 0x45800000, v3
	v_cndmask_b32_e32 v16, v3, v16, vcc
	v_ashrrev_i32_e32 v3, 31, v2
	v_lshlrev_b64 v[2:3], 12, v[2:3]
	v_lshl_add_u64 v[2:3], s[42:43], 0, v[2:3]
	v_lshl_add_u64 v[18:19], v[2:3], 0, v[0:1]
	s_waitcnt vmcnt(5)
	v_lshlrev_b32_e32 v2, 16, v4
	v_and_b32_e32 v3, 0xffff0000, v4
	v_lshlrev_b32_e32 v4, 16, v5
	v_and_b32_e32 v5, 0xffff0000, v5
	v_pk_mul_f32 v[2:3], v[16:17], v[2:3] op_sel_hi:[0,1]
	v_pk_mul_f32 v[4:5], v[16:17], v[4:5] op_sel_hi:[0,1]
	s_waitcnt vmcnt(3)
	v_pk_mul_f32 v[2:3], v[2:3], v[8:9]
	v_pk_mul_f32 v[4:5], v[4:5], v[10:11]
	global_store_dwordx4 v[18:19], v[2:5], off
	v_lshlrev_b32_e32 v8, 16, v6
	v_and_b32_e32 v9, 0xffff0000, v6
	v_lshlrev_b32_e32 v6, 16, v7
	v_and_b32_e32 v7, 0xffff0000, v7
	v_pk_mul_f32 v[8:9], v[16:17], v[8:9] op_sel_hi:[0,1]
	v_pk_mul_f32 v[6:7], v[16:17], v[6:7] op_sel_hi:[0,1]
	s_waitcnt vmcnt(3)
	v_pk_mul_f32 v[2:3], v[8:9], v[200:201]
	v_pk_mul_f32 v[4:5], v[6:7], v[202:203]
	global_store_dwordx4 v[18:19], v[2:5], off offset:16
	v_lshlrev_b32_e32 v6, 16, v212
	v_and_b32_e32 v7, 0xffff0000, v212
	v_lshlrev_b32_e32 v8, 16, v213
	v_and_b32_e32 v9, 0xffff0000, v213
	v_pk_mul_f32 v[6:7], v[16:17], v[6:7] op_sel_hi:[0,1]
	v_pk_mul_f32 v[8:9], v[16:17], v[8:9] op_sel_hi:[0,1]
	s_waitcnt vmcnt(3)
	v_pk_mul_f32 v[2:3], v[6:7], v[204:205]
	v_pk_mul_f32 v[4:5], v[8:9], v[206:207]
	global_store_dwordx4 v[18:19], v[2:5], off offset:32
	v_lshlrev_b32_e32 v6, 16, v214
	v_and_b32_e32 v7, 0xffff0000, v214
	v_lshlrev_b32_e32 v8, 16, v215
	v_and_b32_e32 v9, 0xffff0000, v215
	v_pk_mul_f32 v[6:7], v[16:17], v[6:7] op_sel_hi:[0,1]
	v_pk_mul_f32 v[8:9], v[16:17], v[8:9] op_sel_hi:[0,1]
	s_waitcnt vmcnt(3)
	v_pk_mul_f32 v[2:3], v[6:7], v[208:209]
	v_pk_mul_f32 v[4:5], v[8:9], v[210:211]
	global_store_dwordx4 v[18:19], v[2:5], off offset:48
	s_cbranch_scc1 .LBB0_22
